# ctx_finish (8-slice): norm gain/scale loads issued at loop top, first slice load no longer serialised by a full wait
# baseline (speedup 1.0000x reference)
.LBB0_998:
	global_load_dwordx4 v[104:107], v[10:11], off
	global_load_dwordx4 v[108:111], v[8:9], off
	global_load_dwordx4 v[112:115], v[14:15], off
	global_load_dwordx4 v[116:119], v[8:9], off offset:1024
	global_load_dwordx4 v[120:123], v[18:19], off
	global_load_dwordx4 v[124:127], v[8:9], off offset:2048
	global_load_dwordx4 v[128:131], v[22:23], off
	global_load_dwordx4 v[132:135], v[8:9], off offset:3072
	v_lshl_add_u64 v[30:31], s[42:43], 0, v[28:29]
	v_add_co_u32_e32 v32, vcc, 0x1be00000, v30
	s_nop 1
	v_addc_co_u32_e32 v33, vcc, 0, v31, vcc
	v_add_co_u32_e32 v34, vcc, 0x1c600000, v30
	s_waitcnt lgkmcnt(0)
	global_load_dwordx4 v[0:3], v[32:33], off
	v_addc_co_u32_e32 v35, vcc, 0, v31, vcc
	v_add_co_u32_e32 v36, vcc, 0x1ce00000, v30
	s_nop 1
	v_addc_co_u32_e32 v37, vcc, 0, v31, vcc
	v_add_co_u32_e32 v40, vcc, 0x1d600000, v30
	global_load_dwordx4 v[56:59], v[34:35], off
	global_load_dwordx4 v[60:63], v[36:37], off
	v_addc_co_u32_e32 v41, vcc, 0, v31, vcc
	v_add_co_u32_e32 v42, vcc, 0x1de00000, v30
	s_nop 0
	s_nop 0
	v_addc_co_u32_e32 v43, vcc, 0, v31, vcc
	v_add_co_u32_e32 v44, vcc, 0x1e600000, v30
	global_load_dwordx4 v[64:67], v[40:41], off
	global_load_dwordx4 v[68:71], v[42:43], off
	v_addc_co_u32_e32 v45, vcc, 0, v31, vcc
	v_add_co_u32_e32 v46, vcc, 0x1ee00000, v30
	s_waitcnt vmcnt(3)
	v_pk_add_f32 v[2:3], v[2:3], 0 op_sel_hi:[1,0]
	v_pk_add_f32 v[0:1], v[0:1], 0 op_sel_hi:[1,0]
	v_pk_add_f32 v[2:3], v[2:3], v[58:59]
	v_addc_co_u32_e32 v47, vcc, 0, v31, vcc
	v_add_co_u32_e32 v48, vcc, 0x1f600000, v30
	global_load_dwordx4 v[72:75], v[44:45], off
	global_load_dwordx4 v[76:79], v[46:47], off
	v_addc_co_u32_e32 v49, vcc, 0, v31, vcc
	global_load_dwordx4 v[80:83], v[48:49], off
	v_add_co_u32_e32 v38, vcc, s86, v30
	v_pk_add_f32 v[0:1], v[0:1], v[56:57]
	s_nop 0
	v_addc_co_u32_e32 v39, vcc, 0, v31, vcc
	global_load_dwordx4 v[84:87], v[6:7], off
	global_load_dwordx4 v[88:91], v[38:39], off
	s_waitcnt vmcnt(7)
	v_pk_add_f32 v[2:3], v[2:3], v[62:63]
	v_pk_add_f32 v[0:1], v[0:1], v[60:61]
	s_waitcnt vmcnt(6)
	v_pk_add_f32 v[2:3], v[2:3], v[66:67]
	v_pk_add_f32 v[0:1], v[0:1], v[64:65]
	s_waitcnt vmcnt(5)
	v_pk_add_f32 v[2:3], v[2:3], v[70:71]
	v_pk_add_f32 v[0:1], v[0:1], v[68:69]
	v_add_u32_e32 v30, 0x8000, v4
	v_ashrrev_i32_e32 v31, 31, v30
	v_lshlrev_b64 v[30:31], 11, v[30:31]
	v_lshl_add_u64 v[30:31], v[24:25], 0, v[30:31]
	s_waitcnt vmcnt(4)
	v_pk_add_f32 v[2:3], v[2:3], v[74:75]
	v_pk_add_f32 v[0:1], v[0:1], v[72:73]
	s_waitcnt vmcnt(3)
	v_pk_add_f32 v[2:3], v[2:3], v[78:79]
	v_pk_add_f32 v[0:1], v[0:1], v[76:77]
	s_waitcnt vmcnt(2)
	v_pk_add_f32 v[2:3], v[2:3], v[82:83]
	v_pk_add_f32 v[0:1], v[0:1], v[80:81]
	s_waitcnt vmcnt(0)
	v_pk_fma_f32 v[2:3], v[2:3], v[86:87], v[90:91]
	v_pk_fma_f32 v[0:1], v[0:1], v[84:85], v[88:89]
	global_store_dwordx4 v[38:39], v[0:3], off
	v_pk_add_f32 v[58:59], v[106:107], 1.0 op_sel_hi:[1,0]
	v_pk_add_f32 v[56:57], v[104:105], 1.0 op_sel_hi:[1,0]
	v_pk_mul_f32 v[58:59], v[110:111], v[58:59]
	v_pk_mul_f32 v[56:57], v[108:109], v[56:57]
	v_pk_mul_f32 v[58:59], v[2:3], v[58:59]
	v_pk_mul_f32 v[56:57], v[0:1], v[56:57]
	v_mul_f32_e32 v3, v3, v3
	v_cvt_pk_bf16_f32 v56, v56, v57
	v_cvt_pk_bf16_f32 v57, v58, v59
	global_store_dwordx2 v[30:31], v[56:57], off
	global_load_dwordx4 v[56:59], v[32:33], off offset:1024
	s_nop 0
	global_load_dwordx4 v[60:63], v[34:35], off offset:1024
	global_load_dwordx4 v[64:67], v[36:37], off offset:1024
	global_load_dwordx4 v[68:71], v[40:41], off offset:1024
	global_load_dwordx4 v[72:75], v[42:43], off offset:1024
	global_load_dwordx4 v[76:79], v[44:45], off offset:1024
	global_load_dwordx4 v[80:83], v[46:47], off offset:1024
	global_load_dwordx4 v[84:87], v[48:49], off offset:1024
	global_load_dwordx4 v[88:91], v[38:39], off offset:1024
	global_load_dwordx4 v[92:95], v[12:13], off
	v_mul_f32_e32 v1, v1, v1
	v_fmac_f32_e32 v1, v0, v0
	v_fmac_f32_e32 v3, v2, v2
	v_add_f32_e32 v0, v1, v3
	s_waitcnt vmcnt(9)
	v_pk_add_f32 v[58:59], v[58:59], 0 op_sel_hi:[1,0]
	v_pk_add_f32 v[56:57], v[56:57], 0 op_sel_hi:[1,0]
	s_waitcnt vmcnt(8)
	v_pk_add_f32 v[58:59], v[58:59], v[62:63]
	v_pk_add_f32 v[56:57], v[56:57], v[60:61]
	s_waitcnt vmcnt(7)
	v_pk_add_f32 v[58:59], v[58:59], v[66:67]
	v_pk_add_f32 v[56:57], v[56:57], v[64:65]
	s_waitcnt vmcnt(6)
	v_pk_add_f32 v[58:59], v[58:59], v[70:71]
	v_pk_add_f32 v[56:57], v[56:57], v[68:69]
	s_waitcnt vmcnt(5)
	v_pk_add_f32 v[58:59], v[58:59], v[74:75]
	v_pk_add_f32 v[56:57], v[56:57], v[72:73]
	s_waitcnt vmcnt(4)
	v_pk_add_f32 v[58:59], v[58:59], v[78:79]
	v_pk_add_f32 v[56:57], v[56:57], v[76:77]
	s_waitcnt vmcnt(3)
	v_pk_add_f32 v[58:59], v[58:59], v[82:83]
	v_pk_add_f32 v[56:57], v[56:57], v[80:81]
	s_waitcnt vmcnt(2)
	v_pk_add_f32 v[58:59], v[58:59], v[86:87]
	v_pk_add_f32 v[56:57], v[56:57], v[84:85]
	s_waitcnt vmcnt(0)
	v_pk_fma_f32 v[58:59], v[58:59], v[94:95], v[90:91]
	v_pk_fma_f32 v[56:57], v[56:57], v[92:93], v[88:89]
	global_store_dwordx4 v[38:39], v[56:59], off offset:1024
	v_mul_f32_e32 v1, v57, v57
	v_mul_f32_e32 v2, v59, v59
	v_fmac_f32_e32 v2, v58, v58
	v_fmac_f32_e32 v1, v56, v56
	v_add_f32_e32 v1, v1, v2
	v_add_f32_e32 v0, v0, v1
	v_pk_add_f32 v[62:63], v[114:115], 1.0 op_sel_hi:[1,0]
	v_pk_add_f32 v[60:61], v[112:113], 1.0 op_sel_hi:[1,0]
	v_pk_mul_f32 v[62:63], v[118:119], v[62:63]
	v_pk_mul_f32 v[60:61], v[116:117], v[60:61]
	v_pk_mul_f32 v[62:63], v[58:59], v[62:63]
	v_pk_mul_f32 v[60:61], v[56:57], v[60:61]
	s_nop 0
	v_cvt_pk_bf16_f32 v60, v60, v61
	v_cvt_pk_bf16_f32 v61, v62, v63
	global_store_dwordx2 v[30:31], v[60:61], off offset:512
	global_load_dwordx4 v[60:63], v[32:33], off offset:2048
	s_nop 0
	global_load_dwordx4 v[64:67], v[34:35], off offset:2048
	global_load_dwordx4 v[68:71], v[36:37], off offset:2048
	global_load_dwordx4 v[72:75], v[40:41], off offset:2048
	global_load_dwordx4 v[76:79], v[42:43], off offset:2048
	global_load_dwordx4 v[80:83], v[44:45], off offset:2048
	global_load_dwordx4 v[84:87], v[46:47], off offset:2048
	global_load_dwordx4 v[88:91], v[48:49], off offset:2048
	global_load_dwordx4 v[92:95], v[38:39], off offset:2048
	global_load_dwordx4 v[100:103], v[16:17], off
	s_waitcnt vmcnt(9)
	v_pk_add_f32 v[62:63], v[62:63], 0 op_sel_hi:[1,0]
	v_pk_add_f32 v[60:61], v[60:61], 0 op_sel_hi:[1,0]
	s_waitcnt vmcnt(8)
	v_pk_add_f32 v[62:63], v[62:63], v[66:67]
	v_pk_add_f32 v[60:61], v[60:61], v[64:65]
	s_waitcnt vmcnt(7)
	v_pk_add_f32 v[62:63], v[62:63], v[70:71]
	v_pk_add_f32 v[60:61], v[60:61], v[68:69]
	s_waitcnt vmcnt(6)
	v_pk_add_f32 v[62:63], v[62:63], v[74:75]
	v_pk_add_f32 v[60:61], v[60:61], v[72:73]
	s_waitcnt vmcnt(5)
	v_pk_add_f32 v[62:63], v[62:63], v[78:79]
	v_pk_add_f32 v[60:61], v[60:61], v[76:77]
	s_waitcnt vmcnt(4)
	v_pk_add_f32 v[62:63], v[62:63], v[82:83]
	v_pk_add_f32 v[60:61], v[60:61], v[80:81]
	s_waitcnt vmcnt(3)
	v_pk_add_f32 v[62:63], v[62:63], v[86:87]
	v_pk_add_f32 v[60:61], v[60:61], v[84:85]
	s_waitcnt vmcnt(2)
	v_pk_add_f32 v[62:63], v[62:63], v[90:91]
	v_pk_add_f32 v[60:61], v[60:61], v[88:89]
	s_waitcnt vmcnt(0)
	v_pk_fma_f32 v[62:63], v[62:63], v[102:103], v[94:95]
	v_pk_fma_f32 v[60:61], v[60:61], v[100:101], v[92:93]
	global_store_dwordx4 v[38:39], v[60:63], off offset:2048
	v_mul_f32_e32 v1, v61, v61
	v_mul_f32_e32 v2, v63, v63
	v_fmac_f32_e32 v2, v62, v62
	v_fmac_f32_e32 v1, v60, v60
	v_add_f32_e32 v1, v1, v2
	v_add_f32_e32 v0, v0, v1
	v_pk_add_f32 v[66:67], v[122:123], 1.0 op_sel_hi:[1,0]
	v_pk_add_f32 v[64:65], v[120:121], 1.0 op_sel_hi:[1,0]
	v_pk_mul_f32 v[66:67], v[126:127], v[66:67]
	v_pk_mul_f32 v[64:65], v[124:125], v[64:65]
	v_pk_mul_f32 v[66:67], v[62:63], v[66:67]
	v_pk_mul_f32 v[64:65], v[60:61], v[64:65]
	s_nop 0
	v_cvt_pk_bf16_f32 v64, v64, v65
	v_cvt_pk_bf16_f32 v65, v66, v67
	global_store_dwordx2 v[30:31], v[64:65], off offset:1024
	global_load_dwordx4 v[64:67], v[32:33], off offset:3072
	s_nop 0
	global_load_dwordx4 v[32:35], v[34:35], off offset:3072
	s_nop 0
	global_load_dwordx4 v[68:71], v[36:37], off offset:3072
	global_load_dwordx4 v[72:75], v[40:41], off offset:3072
	s_nop 0
	global_load_dwordx4 v[40:43], v[42:43], off offset:3072
	s_nop 0
	global_load_dwordx4 v[76:79], v[44:45], off offset:3072
	s_nop 0
	global_load_dwordx4 v[44:47], v[46:47], off offset:3072
	s_nop 0
	global_load_dwordx4 v[80:83], v[48:49], off offset:3072
	global_load_dwordx4 v[84:87], v[38:39], off offset:3072
	global_load_dwordx4 v[88:91], v[20:21], off
	s_waitcnt vmcnt(9)
	v_pk_add_f32 v[36:37], v[66:67], 0 op_sel_hi:[1,0]
	v_pk_add_f32 v[48:49], v[64:65], 0 op_sel_hi:[1,0]
	s_waitcnt vmcnt(8)
	v_pk_add_f32 v[34:35], v[36:37], v[34:35]
	v_pk_add_f32 v[32:33], v[48:49], v[32:33]
	s_waitcnt vmcnt(7)
	v_pk_add_f32 v[34:35], v[34:35], v[70:71]
	v_pk_add_f32 v[32:33], v[32:33], v[68:69]
	s_waitcnt vmcnt(6)
	v_pk_add_f32 v[34:35], v[34:35], v[74:75]
	v_pk_add_f32 v[32:33], v[32:33], v[72:73]
	s_waitcnt vmcnt(5)
	v_pk_add_f32 v[34:35], v[34:35], v[42:43]
	v_pk_add_f32 v[32:33], v[32:33], v[40:41]
	s_waitcnt vmcnt(4)
	v_pk_add_f32 v[34:35], v[34:35], v[78:79]
	v_pk_add_f32 v[32:33], v[32:33], v[76:77]
	s_waitcnt vmcnt(3)
	v_pk_add_f32 v[34:35], v[34:35], v[46:47]
	v_pk_add_f32 v[32:33], v[32:33], v[44:45]
	s_waitcnt vmcnt(2)
	v_pk_add_f32 v[34:35], v[34:35], v[82:83]
	v_pk_add_f32 v[32:33], v[32:33], v[80:81]
	s_waitcnt vmcnt(0)
	v_pk_fma_f32 v[34:35], v[34:35], v[90:91], v[86:87]
	v_pk_fma_f32 v[32:33], v[32:33], v[88:89], v[84:85]
	global_store_dwordx4 v[38:39], v[32:35], off offset:3072
	s_nop 0
	v_mul_f32_e32 v1, v33, v33
	v_mul_f32_e32 v2, v35, v35
	v_fmac_f32_e32 v1, v32, v32
	v_fmac_f32_e32 v2, v34, v34
	v_add_f32_e32 v1, v1, v2
	v_add_f32_e32 v0, v0, v1
	ds_bpermute_b32 v1, v50, v0
	s_waitcnt lgkmcnt(0)
	v_add_f32_e32 v0, v0, v1
	ds_bpermute_b32 v1, v51, v0
	s_waitcnt lgkmcnt(0)
	v_add_f32_e32 v0, v0, v1
	ds_bpermute_b32 v1, v52, v0
	s_waitcnt lgkmcnt(0)
	v_add_f32_e32 v0, v0, v1
	ds_bpermute_b32 v1, v53, v0
	s_waitcnt lgkmcnt(0)
	v_add_f32_e32 v0, v0, v1
	ds_bpermute_b32 v1, v54, v0
	s_waitcnt lgkmcnt(0)
	v_add_f32_e32 v0, v0, v1
	ds_bpermute_b32 v1, v55, v0
	v_pk_add_f32 v[2:3], v[130:131], 1.0 op_sel_hi:[1,0]
	v_pk_add_f32 v[36:37], v[128:129], 1.0 op_sel_hi:[1,0]
	v_pk_mul_f32 v[2:3], v[134:135], v[2:3]
	v_pk_mul_f32 v[36:37], v[132:133], v[36:37]
	v_pk_mul_f32 v[2:3], v[34:35], v[2:3]
	v_pk_mul_f32 v[32:33], v[32:33], v[36:37]
	s_nop 0
	v_cvt_pk_bf16_f32 v32, v32, v33
	v_cvt_pk_bf16_f32 v33, v2, v3
	global_store_dwordx2 v[30:31], v[32:33], off offset:1536
	s_and_saveexec_b64 s[8:9], s[38:39]
	s_cbranch_execz .LBB0_997
	s_waitcnt lgkmcnt(0)
	v_add_f32_e32 v2, v0, v1
	v_lshl_add_u64 v[0:1], s[42:43], 0, v[26:27]
	flat_store_dword v[0:1], v2
	s_branch .LBB0_997
